# late-use weight conversion (W_o, W_ffn_up, W_ffn_down f32->bf16 transpose) moved from HBM-bound P0 into the attention K-loop (one row pair per iteration per wave, software-pipelined); Q-resident fragm
# speedup vs baseline: 1.0164x; 1.0093x over previous
; #define LAS __attribute__((address_space(3)))
; __global__ void __launch_bounds__(512, 2) hymba_fwd(Args args) {
;     ...
;     float* SSQ2 = (float*)(ws + WS_SSQ2); float* SSQ3 = (float*)(ws + WS_SSQ3); float* ROPE = (float*)(ws + WS_ROPE); float* CWS = (float*)(ws + WS_CWS);
;     bf16_t* KPE = (bf16_t*)(ws + WS_KPE); float* HALO = (float*)(ws + WS_HALO);
;     bf16_t* WinT = (bf16_t*)(ws + WS_WIN); bf16_t* WqT = (bf16_t*)(ws + WS_WQ); bf16_t* WkvT = (bf16_t*)(ws + WS_WKV); bf16_t* WoT = (bf16_t*)(ws + WS_WO);
;     bf16_t* WupT = (bf16_t*)(ws + WS_WUP); bf16_t* WdT = (bf16_t*)(ws + WS_WD);
;     bf16_t* XB = (bf16_t*)(ws + WS_XB); bf16_t* ZA = (bf16_t*)(ws + WS_ZA); bf16_t* Gb = (bf16_t*)(ws + WS_G); bf16_t* MG = (bf16_t*)(ws + WS_MERGED);
;     bf16_t* A2 = (bf16_t*)(ws + WS_A2); bf16_t* Qb = (bf16_t*)(ws + WS_Q); bf16_t* KVb = (bf16_t*)(ws + WS_KV); bf16_t* X1B = (bf16_t*)(ws + WS_X1B);
;     ...
;     const int gw = vcu * 8 + wave, NGW = G * 8;
;     if (IN(0)) for (int rep_ = 0; rep_ < REPS(0); ++rep_) {
;         LAS float* scr = (LAS float*)(lds + RING_OFF + wave * 16384);
;         {
;             const P0Ptrs pa{w_o, on_a, on_c, w_up, ffn_g, w_dn, w_in, attn_g, w_qb, qa_g, w_kvb, kva_g, WoT, WupT, WdT, WinT, WqT, WkvT};
;             for (int it = gw; it < NFAST / 4; it += NGW) p0_batch<4>(it, 0, lane, pa);
.LBB0_9:
	v_writelane_b32 v247, s0, 5
	s_add_u32 s0, s28, 0x3500000
	s_addc_u32 s1, s29, 0
	v_writelane_b32 v247, s0, 6
	v_and_b32_e32 v225, 63, v0
	s_nop 0
	v_writelane_b32 v247, s1, 7
	s_add_u32 s0, s28, 0x6900000
	s_addc_u32 s1, s29, 0
	v_writelane_b32 v247, s0, 8
	s_nop 1
	v_writelane_b32 v247, s1, 9
	s_add_u32 s0, s28, 0x800000
	s_addc_u32 s1, s29, 0
	s_add_u32 s66, s28, 0x1600000
	v_writelane_b32 v247, s0, 10
	s_addc_u32 s67, s29, 0
	s_nop 0
	v_writelane_b32 v247, s1, 11
	s_add_u32 s0, s28, 0x2700000
	s_addc_u32 s1, s29, 0
	v_writelane_b32 v247, s0, 12
	s_nop 1
	v_writelane_b32 v247, s1, 13
	s_add_u32 s0, s28, 0x2d00000
	s_addc_u32 s1, s29, 0
	v_writelane_b32 v247, s0, 14
	s_nop 1
	v_writelane_b32 v247, s1, 15
	s_add_u32 s0, s28, 0x3d00000
	s_addc_u32 s1, s29, 0
	v_writelane_b32 v247, s0, 16
	s_lshr_b32 s34, s3, 6
	s_lshl_b32 s97, s33, 3
	v_writelane_b32 v247, s1, 17
	s_lshl_b32 s0, s2, 3
	s_add_i32 s52, s0, s34
	s_cmp_lt_i32 s30, 1
	s_cselect_b64 s[0:1], -1, 0
	s_cmp_gt_i32 s31, 0
	s_cselect_b64 s[4:5], -1, 0
	s_and_b64 s[68:69], s[0:1], s[4:5]
	s_andn2_b64 vcc, exec, s[68:69]
	s_cbranch_vccnz .LBB0_200
	s_lshl_b32 s56, s34, 8
	s_add_i32 s56, s56, s2
	s_addk_i32 s56, 0x1280
	s_cmpk_gt_i32 s56, 0x173f
	s_cbranch_scc1 .LBB0_128
	s_add_u32 s35, s10, 0xfffff000
	v_and_b32_e32 v1, 28, v224
	v_and_b32_e32 v172, 56, v0
	s_addc_u32 s11, s11, -1
	s_movk_i32 s53, 0x840
	v_mov_b32_e32 v163, 0
	v_mov_b32_e32 v173, s15
	v_mov_b32_e32 v174, s14
	v_mov_b32_e32 v175, 0x7c
	s_branch .LBB0_13

; template <int ABL> __device__ __forceinline__ void attn_unit(int b, int h, int qb, const bf16_t* Q, const bf16_t* KV, const bf16_t* KPE, bf16_t* MG, float* ssqa, LAS unsigned char* L) {
;   const int tid = threadIdx.x, lane = fresh_lane(), r32 = lane & 31, hi = lane >> 5; const int wid = __builtin_amdgcn_readfirstlane(tid >> 6);
;   LAS unsigned char* Vl = L + OFF_V; LAS unsigned char* Kl = L + OFF_K;
;   LAS float* wsf = (LAS float*)(L + OFF_WS) + wid * 64; LAS float* li_l = wsf; LAS float* al_l = wsf + 32;
;   LAS unsigned char* Qr = (wid < 5) ? L + OFF_QR + wid * 8192 : L + OFF_QR_HI + (wid - 5) * 8192;
;   float m_reg = -1e30f, l_reg = 0; f32x16 o[4] = {}; bf16x8 qr[4];
;   const size_t rowbase = (size_t)b * SEQ; const int q0 = qb * 256;
;   const int kro = r32 * 128, ksw = (r32 >> 1) & 7;
;   const int krow = wid * 8 + (lane >> 3), kcl = (lane & 7) ^ ((krow >> 1) & 7);
;   const unsigned voffK = (unsigned)(krow * LDKV + kcl * 8) * 2u, voffP = (unsigned)(krow * LDKPE + kcl * 8) * 2u;
;   const int vj = (lane >> 2) & 7, vkg = wid >> 1, vk = (vkg >> 1) * 16 + (vj >> 2) * 8 + (vkg & 1) * 4 + (vj & 3), vc = 32 * (2 * (wid & 1) + (lane >> 5)) + (lane & 3) * 8;
;   const unsigned voffV = (unsigned)(vk * LDKV + vc) * 2u;
;   const char* Kt = (const char*)(KV + rowbase * LDKV + h * 256); const char* Pt = (const char*)(KPE + rowbase * LDKPE);
;   constexpr size_t KSTEP = (size_t)KVBLK * LDKV * 2, PSTEP = (size_t)KVBLK * LDKPE * 2;
;     ...
;   DMA_K(0, 0); DMA_V(0, 0); DMA_K(1, 1);
;   const bf16_t* Qw = Q + (rowbase + q0 + wid * QBLK + r32) * LDQ + h * 192 + hi * 8;
; #pragma unroll
;   for (int d0 = 0; d0 < 4; ++d0) qr[d0] = ld8(Qw + d0 * 16);
; #pragma unroll
;   for (int dd = 0; dd < 8; ++dd) *reinterpret_cast<LAS bf16x8*>(Qr + (dd >> 2) * 4096 + kro + (((2 * (dd & 3) + hi) ^ ksw) << 4)) = ld8(Qw + (4 + dd) * 16);
; template <int NB>
; __device__ __forceinline__ void p0_batch(int it0, int stride, int lane, const P0Ptrs& a) {
;     f32x4 v[NB][8], s0[NB], s1[NB]; P0Desc d[NB];
; #pragma unroll
;     for (int q = 0; q < NB; ++q) { const bool ok = it0 < NFAST / 4; d[q] = p0_desc(p0_super(ok ? it0 : 0, q), lane, a); if (!ok) d[q].dst = nullptr;
; #pragma unroll
;         for (int i = 0; i < 8; ++i) v[q][i] = __builtin_nontemporal_load((const f32x4*)(d[q].src + (size_t)i * d[q].nsrc));
;         const float* kp = d[q].ks ? d[q].ks : a.ffn_g;
.LBB0_746:
	v_readlane_b32 s100, v247, 0
	v_readlane_b32 s101, v247, 1
	s_mov_b32 s87, 0
	s_lshr_b32 s99, s2, 8
	s_mul_i32 s99, s99, 5
	s_add_i32 s32, s99, -1
	s_sub_u32 s100, s100, 0xa0
	s_subb_u32 s101, s101, 0
	s_movk_i32 s98, 0x78
	s_cmp_lt_u32 s99, 7
	s_cselect_b32 s98, 0x60, s98
	s_cmp_eq_u32 s99, 0
	s_cselect_b32 s98, 0x50, s98
	s_cselect_b32 s99, 0, 0x58
	s_load_dwordx2 s[88:89], s[100:101], s98
	s_cmp_eq_u32 s99, 0
	s_cbranch_scc0 .Lcv_s1b_u
	s_bfe_u32 s99, s2, 0x50003
	s_cmp_lt_u32 s99, 16
	s_cselect_b32 s99, 64, 0x48
.Lcv_s1b_u:
	s_load_dwordx2 s[94:95], s[100:101], s99
	v_readfirstlane_b32 s82, v0
	s_ashr_i32 s54, s2, 7
	s_lshr_b32 s58, s82, 4
	s_lshr_b32 s83, s82, 6
	s_ashr_i32 s55, s54, 31
	s_lshl_b32 s6, s2, 8
	s_and_b32 s84, s58, 0xffff0
	s_lshr_b32 s58, s82, 5
	s_bfe_u32 s56, s2, 0x30004
	v_mbcnt_lo_u32_b32 v56, -1, 0
	v_mbcnt_hi_u32_b32 v56, -1, v56
	s_lshl_b32 s57, s83, 13
	v_ashrrev_i32_e32 v164, 5, v56
	s_lshl_b64 s[0:1], s[54:55], 12
	s_and_b32 s6, s6, 0xf00
	s_and_b32 s85, s58, 4
	s_and_b32 s58, s58, 2
	s_lshl_b64 s[72:73], s[54:55], 24
	v_ashrrev_i32_e32 v57, 3, v56
	v_add_u32_e32 v6, s58, v164
	s_add_u32 s58, s36, s72
	v_lshl_add_u32 v4, s83, 3, v57
	s_addc_u32 s59, s37, s73
	s_lshl_b32 s60, s56, 9
	v_lshrrev_b32_e32 v2, 1, v4
	s_add_u32 s70, s58, s60
	v_xor_b32_e32 v2, v2, v56
	s_addc_u32 s71, s59, 0
	s_lshl_b64 s[74:75], s[54:55], 19
	v_lshlrev_b32_e32 v2, 4, v2
	s_add_u32 s54, s22, s74
	v_and_b32_e32 v58, 0x70, v2
	s_addc_u32 s55, s23, s75
	s_lshl_b32 s86, s83, 10
	v_lshrrev_b32_e32 v1, 1, v56
	v_lshl_or_b32 v2, v4, 12, v58
	s_add_i32 s58, s86, 0
	v_and_b32_e32 v59, 8, v1
	v_bfe_u32 v60, v56, 2, 2
	v_lshlrev_b32_e32 v62, 4, v56
	s_add_i32 s59, s58, 0x8000
	v_lshl_add_u64 v[52:53], s[70:71], 0, v[2:3]
	s_mov_b64 s[60:61], 0x80
	v_or3_b32 v5, v59, v60, s84
	v_and_b32_e32 v61, 48, v62
	s_mov_b32 m0, s59
	v_lshl_add_u64 v[8:9], v[52:53], 0, s[60:61]
	s_add_i32 s60, s58, 0xa000
	v_or_b32_e32 v5, s85, v5
	v_lshl_or_b32 v6, v6, 6, v61
	global_load_lds_dwordx4 v2, s[70:71]
	s_mov_b32 m0, s60
	s_add_i32 s61, s58, 0xc000
	v_lshl_or_b32 v4, v4, 7, v58
	v_lshl_add_u32 v6, v5, 12, v6
	global_load_lds_dwordx4 v[8:9], off
	v_mov_b32_e32 v5, v3
	s_mov_b32 m0, s61
	v_mov_b32_e32 v7, v3
	v_lshl_add_u64 v[54:55], s[54:55], 0, v[4:5]
	global_load_lds_dwordx4 v4, s[54:55]
	v_lshl_add_u64 v[142:143], s[70:71], 0, v[6:7]
	s_mov_b64 s[54:55], 0x100
	v_lshl_add_u64 v[4:5], v[142:143], 0, s[54:55]
	s_mov_b32 m0, s58
	s_mov_b64 s[54:55], 0x20100
	s_add_i32 s77, s58, 0x2000
	global_load_lds_dwordx4 v[4:5], off
	v_lshl_add_u64 v[4:5], v[142:143], 0, s[54:55]
	s_mov_b32 m0, s77
	s_add_i32 s78, s58, 0xe000
	s_mov_b64 s[54:55], 0x40000
	global_load_lds_dwordx4 v[4:5], off
	v_lshl_add_u64 v[4:5], v[52:53], 0, s[54:55]
	s_mov_b32 m0, s78
	s_mov_b64 s[54:55], 0x40080
	global_load_lds_dwordx4 v[4:5], off
	v_lshl_add_u64 v[4:5], v[52:53], 0, s[54:55]
	s_add_i32 m0, s58, 0x10000
	s_or_b32 s0, s0, s6
	global_load_lds_dwordx4 v[4:5], off
	s_add_i32 m0, s58, 0x12000
	s_lshl_b32 s6, s83, 5
	v_and_b32_e32 v163, 31, v56
	s_mov_b64 s[54:55], 0x2000
	s_add_u32 s70, s0, s6
	v_lshl_add_u64 v[4:5], v[54:55], 0, s[54:55]
	v_or_b32_e32 v2, s70, v163
	s_movk_i32 s0, 0xc00
	global_load_lds_dwordx4 v[4:5], off
	s_addc_u32 s71, s1, 0
	v_mad_u64_u32 v[4:5], s[0:1], v2, s0, v[138:139]
	v_mad_i32_i24 v5, s71, v141, v5
	s_mul_i32 s6, s56, 0x180
	v_lshlrev_b32_e32 v6, 3, v164
	v_lshl_add_u64 v[4:5], v[4:5], 0, s[6:7]
	v_ashrrev_i32_e32 v7, 31, v6
	v_lshl_add_u64 v[8:9], v[6:7], 1, v[4:5]
	global_load_dwordx4 v[126:129], v[8:9], off
	global_load_dwordx4 v[122:125], v[8:9], off offset:32
	global_load_dwordx4 v[118:121], v[8:9], off offset:64
	global_load_dwordx4 v[114:117], v[8:9], off offset:96
	global_load_dwordx4 v[4:7], v[8:9], off offset:128
	s_add_i32 s6, s57, 0
	s_cmpk_lt_u32 s82, 0x140
	s_mov_b32 s0, 0x14800
	s_cselect_b32 s0, s0, 0x16400
	s_add_i32 s0, s6, s0
	v_lshlrev_b32_e32 v63, 7, v163
	v_bitop3_b32 v10, v1, v164, 7 bitop3:0x6c
	v_add_u32_e32 v2, s0, v63
	v_lshlrev_b32_e32 v172, 4, v10
	v_add_u32_e32 v171, v2, v172
	v_add_u32_e32 v10, 2, v164
	v_bitop3_b32 v10, v10, v1, 7 bitop3:0x78
	v_lshlrev_b32_e32 v173, 4, v10
	v_add_u32_e32 v170, v2, v173
	v_add_u32_e32 v10, 4, v164
	v_bitop3_b32 v10, v10, v1, 7 bitop3:0x78
	v_lshlrev_b32_e32 v174, 4, v10
	v_add_u32_e32 v169, v2, v174
	v_add_u32_e32 v10, 6, v164
	v_bitop3_b32 v1, v10, v1, 7 bitop3:0x78
	v_lshlrev_b32_e32 v175, 4, v1
	v_add_u32_e32 v168, v2, v175
	v_add_u32_e32 v1, 0, v63
	v_add_u32_e32 v178, v1, v172
	s_waitcnt vmcnt(0)
	ds_write_b128 v171, v[4:7]
	global_load_dwordx4 v[4:7], v[8:9], off offset:160
	s_waitcnt vmcnt(0)
	ds_write_b128 v170, v[4:7]
	global_load_dwordx4 v[4:7], v[8:9], off offset:192
	s_waitcnt vmcnt(0)
	ds_write_b128 v169, v[4:7]
	global_load_dwordx4 v[4:7], v[8:9], off offset:224
	s_waitcnt vmcnt(0)
	ds_write_b128 v168, v[4:7]
	global_load_dwordx4 v[4:7], v[8:9], off offset:256
	s_waitcnt vmcnt(0)
	ds_write_b128 v171, v[4:7] offset:4096
	global_load_dwordx4 v[4:7], v[8:9], off offset:288
	s_waitcnt vmcnt(0)
	ds_write_b128 v170, v[4:7] offset:4096
	global_load_dwordx4 v[4:7], v[8:9], off offset:320
	s_waitcnt vmcnt(0)
	ds_write_b128 v169, v[4:7] offset:4096
	global_load_dwordx4 v[4:7], v[8:9], off offset:352
	s_waitcnt vmcnt(0)
	ds_write_b128 v168, v[4:7] offset:4096
	s_waitcnt vmcnt(0)
	s_waitcnt lgkmcnt(0)
	s_barrier
	ds_read_b128 v[4:7], v178 offset:32768
	ds_read_b128 v[8:11], v178 offset:36864
	s_waitcnt lgkmcnt(1)
	v_mfma_f32_32x32x16_bf16 v[36:51], v[4:7], v[126:129], 0
	v_add_u32_e32 v179, v1, v173
	ds_read_b128 v[12:15], v179 offset:32768
	ds_read_b128 v[16:19], v179 offset:36864
	s_waitcnt lgkmcnt(2)
	v_mfma_f32_32x32x16_bf16 v[20:35], v[8:11], v[126:129], 0
	s_waitcnt lgkmcnt(1)
	v_mfma_f32_32x32x16_bf16 v[36:51], v[12:15], v[122:125], v[36:51]
	v_add_u32_e32 v177, v1, v174
	ds_read_b128 v[4:7], v177 offset:32768
	ds_read_b128 v[8:11], v177 offset:36864
	s_waitcnt lgkmcnt(2)
	v_mfma_f32_32x32x16_bf16 v[20:35], v[16:19], v[122:125], v[20:35]
	s_waitcnt lgkmcnt(1)
	v_mfma_f32_32x32x16_bf16 v[36:51], v[4:7], v[118:121], v[36:51]
	v_add_u32_e32 v176, v1, v175
	ds_read_b128 v[12:15], v176 offset:32768
	ds_read_b128 v[16:19], v176 offset:36864
	s_waitcnt lgkmcnt(2)
	v_mfma_f32_32x32x16_bf16 v[20:35], v[8:11], v[118:121], v[20:35]
	s_waitcnt lgkmcnt(1)
	v_mfma_f32_32x32x16_bf16 v[36:51], v[12:15], v[114:117], v[36:51]
	ds_read_b128 v[4:7], v178 offset:40960
	ds_read_b128 v[8:11], v178 offset:45056
	ds_read_b128 v[64:67], v171
	s_waitcnt lgkmcnt(3)
	v_mfma_f32_32x32x16_bf16 v[20:35], v[16:19], v[114:117], v[20:35]
	s_waitcnt lgkmcnt(0)
	v_mfma_f32_32x32x16_bf16 v[36:51], v[4:7], v[64:67], v[36:51]
	ds_read_b128 v[12:15], v179 offset:40960
	ds_read_b128 v[16:19], v179 offset:45056
	ds_read_b128 v[68:71], v170
	v_mfma_f32_32x32x16_bf16 v[20:35], v[8:11], v[64:67], v[20:35]
	s_waitcnt lgkmcnt(0)
	v_mfma_f32_32x32x16_bf16 v[36:51], v[12:15], v[68:71], v[36:51]
	ds_read_b128 v[4:7], v177 offset:40960
	ds_read_b128 v[8:11], v177 offset:45056
	ds_read_b128 v[64:67], v169
	v_mfma_f32_32x32x16_bf16 v[20:35], v[16:19], v[68:71], v[20:35]
	s_waitcnt lgkmcnt(0)
	v_mfma_f32_32x32x16_bf16 v[36:51], v[4:7], v[64:67], v[36:51]
	ds_read_b128 v[12:15], v176 offset:40960
	ds_read_b128 v[16:19], v176 offset:45056
	ds_read_b128 v[68:71], v168
	v_mfma_f32_32x32x16_bf16 v[20:35], v[8:11], v[64:67], v[20:35]
	s_waitcnt lgkmcnt(0)
	v_mfma_f32_32x32x16_bf16 v[36:51], v[12:15], v[68:71], v[36:51]
	ds_read_b128 v[4:7], v178 offset:49152
	ds_read_b128 v[8:11], v178 offset:53248
	ds_read_b128 v[64:67], v171 offset:4096
	v_mfma_f32_32x32x16_bf16 v[20:35], v[16:19], v[68:71], v[20:35]
	s_waitcnt lgkmcnt(0)
	v_mfma_f32_32x32x16_bf16 v[36:51], v[4:7], v[64:67], v[36:51]
	ds_read_b128 v[12:15], v179 offset:49152
	ds_read_b128 v[16:19], v179 offset:53248
	ds_read_b128 v[68:71], v170 offset:4096
	v_mfma_f32_32x32x16_bf16 v[20:35], v[8:11], v[64:67], v[20:35]
	s_waitcnt lgkmcnt(0)
	v_mfma_f32_32x32x16_bf16 v[36:51], v[12:15], v[68:71], v[36:51]
	ds_read_b128 v[4:7], v177 offset:49152
	ds_read_b128 v[8:11], v177 offset:53248
	ds_read_b128 v[64:67], v169 offset:4096
	v_mfma_f32_32x32x16_bf16 v[20:35], v[16:19], v[68:71], v[20:35]
	s_waitcnt lgkmcnt(0)
	v_mfma_f32_32x32x16_bf16 v[36:51], v[4:7], v[64:67], v[36:51]
	ds_read_b128 v[12:15], v176 offset:49152
	ds_read_b128 v[16:19], v176 offset:53248
	ds_read_b128 v[68:71], v168 offset:4096
	v_mfma_f32_32x32x16_bf16 v[20:35], v[8:11], v[64:67], v[20:35]
	s_waitcnt lgkmcnt(0)
	v_mfma_f32_32x32x16_bf16 v[36:51], v[12:15], v[68:71], v[36:51]
	v_mfma_f32_32x32x16_bf16 v[20:35], v[16:19], v[68:71], v[20:35]
	s_nop 10
	v_max_f32_e32 v1, v37, v37
	v_max_f32_e32 v2, v36, v36
	v_max_f32_e32 v1, v2, v1
	v_max3_f32 v2, v38, v39, v21
	v_max3_f32 v1, v1, v20, v22
	v_max3_f32 v1, v1, v23, v40
	v_max3_f32 v2, v2, v42, v43
	v_max3_f32 v1, v1, v41, v24
	v_max3_f32 v2, v2, v26, v27
	v_max3_f32 v1, v1, v25, v44
	v_max3_f32 v2, v2, v46, v47
	v_max3_f32 v1, v1, v45, v28
	v_max3_f32 v2, v2, v30, v31
	v_max3_f32 v1, v1, v29, v48
	v_max3_f32 v2, v2, v50, v51
	v_max3_f32 v1, v1, v49, v32
	v_max3_f32 v2, v2, v34, v35
	v_max3_f32 v1, v1, v33, v2
	v_mov_b32_e32 v2, v1
	s_nop 1
	v_permlane32_swap_b32_e32 v1, v2
	v_max_f32_e32 v2, v2, v2
	v_max_f32_e32 v1, v1, v1
	v_max_f32_e32 v1, v1, v2
	v_add_f32_e32 v2, 0x7149f2ca, v1
	v_cmp_ge_f32_e32 vcc, s3, v2
	s_cmp_eq_u64 vcc, exec
	s_cbranch_scc0 .LBB0_794
	v_mov_b32_e32 v140, 0xf149f2ca
	v_mov_b32_e32 v180, 1.0

; template <int G> __device__ __forceinline__ void fin_gap(f32x16& P0, f32x16& P1, float (&sacc)[4], unsigned (&cv)[16], u32x4 (&pw)[4]) {
;   if constexpr (G < 16) { P1[G] = __builtin_amdgcn_exp2f(P1[G]); sacc[G & 3] += P0[G]; }
;   else { constexpr int r = 2 * (G - 16); sacc[r & 3] += P1[r]; sacc[(r + 1) & 3] += P1[r + 1]; }
;   if constexpr (G < 4) cv[G] = cvtpk_c(P0[2 * G], P0[2 * G + 1]);
;   else if constexpr (G >= 6 && G < 10) { constexpr int i = G - 2; cv[i] = cvtpk_c(P0[2 * i], P0[2 * i + 1]); }
;   else if constexpr (G >= 12 && G < 16) { constexpr int i = G - 4, j = i - 8; cv[i] = cvtpk_c(P1[2 * j], P1[2 * j + 1]); }
;   else if constexpr (G >= 18 && G < 22) { constexpr int i = G - 6, j = i - 8; cv[i] = cvtpk_c(P1[2 * j], P1[2 * j + 1]); }
;   if constexpr (G == 4 || G == 10 || G == 16 || G == 22) { constexpr int q = (G - 4) / 6; auto r0 = __builtin_amdgcn_permlane32_swap(cv[4 * q], cv[4 * q + 2], false, false); pw[q].x = r0[0]; pw[q].z = r0[1]; }
;   if constexpr (G == 5 || G == 11 || G == 17 || G == 23) { constexpr int q = (G - 5) / 6; auto r1 = __builtin_amdgcn_permlane32_swap(cv[4 * q + 1], cv[4 * q + 3], false, false); pw[q].y = r1[0]; pw[q].w = r1[1]; }
; }
.LBB0_754:
	ds_read_b128 v[70:73], v178 offset:57344
	ds_read_b128 v[74:77], v178 offset:61440
	s_waitcnt lgkmcnt(0)
	ds_read_b128 v[134:137], v179 offset:57344
	ds_read_b128 v[186:189], v179 offset:61440
	v_mfma_f32_32x32x16_bf16 v[84:99], v[70:73], v[126:129], 0
	v_exp_f32_e32 v210, v130
	v_add_f32_e32 v185, 0, v68
	v_cvt_pk_bf16_f32 v130, v68, v1
	v_mfma_f32_32x32x16_bf16 v[68:83], v[74:77], v[126:129], 0
	v_exp_f32_e32 v211, v131
	v_add_f32_e32 v1, 0, v1
	v_cvt_pk_bf16_f32 v131, v112, v113
	s_waitcnt lgkmcnt(0)
	ds_read_b128 v[190:193], v177 offset:57344
	ds_read_b128 v[194:197], v177 offset:61440
	v_mfma_f32_32x32x16_bf16 v[84:99], v[134:137], v[122:125], v[84:99]
	v_exp_f32_e32 v212, v132
	v_add_f32_e32 v202, 0, v112
	v_cvt_pk_bf16_f32 v132, v110, v111
	v_mfma_f32_32x32x16_bf16 v[68:83], v[186:189], v[122:125], v[68:83]
	v_exp_f32_e32 v213, v133
	v_add_f32_e32 v203, 0, v113
	v_cvt_pk_bf16_f32 v133, v108, v109
	s_waitcnt lgkmcnt(0)
	ds_read_b128 v[134:137], v176 offset:57344
	ds_read_b128 v[198:201], v176 offset:61440
	v_mfma_f32_32x32x16_bf16 v[84:99], v[190:193], v[118:121], v[84:99]
	v_add_f32_e32 v189, v110, v185
	v_permlane32_swap_b32_e32 v130, v132
	v_exp_f32_e32 v214, v160
	v_mfma_f32_32x32x16_bf16 v[68:83], v[194:197], v[118:121], v[68:83]
	v_add_f32_e32 v1, v111, v1
	v_permlane32_swap_b32_e32 v131, v133
	v_exp_f32_e32 v215, v161
	s_waitcnt lgkmcnt(0)
	v_add_u32_e32 v185, v181, v172
	v_add_u32_e32 v186, v182, v172
	ds_read_b128 v[110:113], v185
	ds_read_b128 v[190:193], v186
	ds_read_b128 v[194:197], v171
	v_mfma_f32_32x32x16_bf16 v[84:99], v[134:137], v[114:117], v[84:99]
	v_add_f32_e32 v217, v108, v202
	v_cvt_pk_bf16_f32 v108, v106, v107
	v_exp_f32_e32 v216, v158
	v_mfma_f32_32x32x16_bf16 v[68:83], v[198:201], v[114:117], v[68:83]
	v_add_f32_e32 v219, v109, v203
	v_cvt_pk_bf16_f32 v109, v104, v105
	v_exp_f32_e32 v218, v159
	s_waitcnt lgkmcnt(0)
	v_add_u32_e32 v187, v181, v173
	v_add_u32_e32 v188, v182, v173
	ds_read_b128 v[134:137], v187
	ds_read_b128 v[158:161], v188
	ds_read_b128 v[198:201], v170
	v_mfma_f32_32x32x16_bf16 v[84:99], v[110:113], v[194:197], v[84:99]
	v_cvt_pk_bf16_f32 v110, v102, v103
	v_exp_f32_e32 v220, v156
	v_add_f32_e32 v112, v106, v189
	v_mfma_f32_32x32x16_bf16 v[68:83], v[190:193], v[194:197], v[68:83]
	v_add_f32_e32 v1, v107, v1
	v_cvt_pk_bf16_f32 v111, v100, v101
	v_exp_f32_e32 v113, v157
	s_waitcnt lgkmcnt(0)
	v_add_u32_e32 v189, v181, v174
	v_add_u32_e32 v190, v182, v174
	ds_read_b128 v[194:197], v189
	ds_read_b128 v[202:205], v190
	ds_read_b128 v[206:209], v169
	v_mfma_f32_32x32x16_bf16 v[84:99], v[134:137], v[198:201], v[84:99]
	v_permlane32_swap_b32_e32 v108, v110
	v_exp_f32_e32 v221, v154
	v_add_f32_e32 v217, v104, v217
	v_mfma_f32_32x32x16_bf16 v[68:83], v[158:161], v[198:201], v[68:83]
	v_permlane32_swap_b32_e32 v109, v111
	v_exp_f32_e32 v222, v155
	v_add_f32_e32 v219, v105, v219
	s_waitcnt lgkmcnt(0)
	v_add_u32_e32 v191, v181, v175
	v_add_u32_e32 v192, v182, v175
	ds_read_b128 v[104:107], v191
	ds_read_b128 v[134:137], v192
	ds_read_b128 v[154:157], v168
	v_mfma_f32_32x32x16_bf16 v[84:99], v[194:197], v[206:209], v[84:99]
	v_add_f32_e32 v112, v102, v112
	v_cvt_pk_bf16_f32 v102, v210, v211
	v_exp_f32_e32 v223, v152
	v_mfma_f32_32x32x16_bf16 v[68:83], v[202:205], v[206:209], v[68:83]
	v_add_f32_e32 v1, v103, v1
	v_cvt_pk_bf16_f32 v103, v212, v213
	v_exp_f32_e32 v226, v153
	s_waitcnt lgkmcnt(0)
	v_add_u32_e32 v193, v183, v172
	v_add_u32_e32 v194, v184, v172
	ds_read_b128 v[158:161], v193
	ds_read_b128 v[198:201], v194
	ds_read_b128 v[202:205], v171 offset:4096
	v_mfma_f32_32x32x16_bf16 v[84:99], v[104:107], v[154:157], v[84:99]
	v_cvt_pk_bf16_f32 v104, v214, v215
	v_exp_f32_e32 v227, v150
	v_add_f32_e32 v100, v100, v217
	v_mfma_f32_32x32x16_bf16 v[68:83], v[134:137], v[154:157], v[68:83]
	v_cvt_pk_bf16_f32 v105, v216, v218
	v_exp_f32_e32 v106, v151
	v_add_f32_e32 v101, v101, v219
	s_waitcnt lgkmcnt(0)
	v_add_u32_e32 v195, v183, v173
	v_add_u32_e32 v196, v184, v173
	ds_read_b128 v[134:137], v195
	ds_read_b128 v[150:153], v196
	ds_read_b128 v[154:157], v170 offset:4096
	v_mfma_f32_32x32x16_bf16 v[84:99], v[158:161], v[202:205], v[84:99]
	v_add_f32_e32 v1, v211, v1
	v_permlane32_swap_b32_e32 v102, v104
	v_add_f32_e32 v107, v210, v112
	v_mfma_f32_32x32x16_bf16 v[68:83], v[198:201], v[202:205], v[68:83]
	v_permlane32_swap_b32_e32 v103, v105
	v_add_f32_e32 v100, v212, v100
	v_add_f32_e32 v101, v213, v101
	s_waitcnt lgkmcnt(0)
	v_add_u32_e32 v197, v183, v174
	v_add_u32_e32 v198, v184, v174
	ds_read_b128 v[158:161], v197
	ds_read_b128 v[202:205], v198
	ds_read_b128 v[206:209], v169 offset:4096
	v_mfma_f32_32x32x16_bf16 v[84:99], v[134:137], v[154:157], v[84:99]
	v_add_f32_e32 v1, v215, v1
	v_cvt_pk_bf16_f32 v134, v220, v113
	v_add_f32_e32 v107, v214, v107
	v_mfma_f32_32x32x16_bf16 v[68:83], v[150:153], v[154:157], v[68:83]
	v_cvt_pk_bf16_f32 v135, v221, v222
	v_add_f32_e32 v100, v216, v100
	v_add_f32_e32 v101, v218, v101
	s_waitcnt lgkmcnt(0)
	v_add_u32_e32 v199, v183, v175
	v_add_u32_e32 v200, v184, v175
	ds_read_b128 v[150:153], v199
	ds_read_b128 v[154:157], v200
	ds_read_b128 v[210:213], v168 offset:4096
	v_mfma_f32_32x32x16_bf16 v[84:99], v[158:161], v[206:209], v[84:99]
	v_add_f32_e32 v1, v113, v1
	v_cvt_pk_bf16_f32 v136, v223, v226
	v_add_f32_e32 v107, v220, v107
	v_mfma_f32_32x32x16_bf16 v[68:83], v[202:205], v[206:209], v[68:83]
	v_cvt_pk_bf16_f32 v137, v227, v106
	v_add_f32_e32 v100, v221, v100
	v_add_f32_e32 v101, v222, v101
	s_waitcnt lgkmcnt(0)
	v_mfma_f32_32x32x16_bf16 v[84:99], v[150:153], v[210:213], v[84:99]
	v_add_f32_e32 v1, v226, v1
	v_permlane32_swap_b32_e32 v134, v136
	v_add_f32_e32 v107, v223, v107
	v_mfma_f32_32x32x16_bf16 v[68:83], v[154:157], v[210:213], v[68:83]
	v_permlane32_swap_b32_e32 v135, v137
	v_add_f32_e32 v100, v227, v100
	v_add_f32_e32 v101, v106, v101
	v_add_f32_e32 v1, v107, v1
	v_add_f32_e32 v100, v100, v101
	v_add_f32_e32 v201, v1, v100
	v_mov_b32_e32 v202, v201
	s_nop 1
	v_permlane32_swap_b32_e32 v201, v202

; __device__ __forceinline__ P0Desc p0_desc(int r, int lane, const P0Ptrs& a) {
;     const int kk = lane >> 3, n4 = (lane & 7) * 4; P0Desc d; d.gs = 1.f;
;     int kb, n, sc, nsrc, ldt; const float* W; bf16_t* WT; const float* ks;
;     if (r < F_O) { kb = r >> 6; n = 32 * (r & 63) + n4; sc = n; W = a.w_o; nsrc = 2048; WT = a.WoT; ldt = 2048; ks = (kb < 16) ? a.on_a : (a.on_c - 1024); }
;     else if ((r -= F_O) < F_UP) { kb = r / 352; n = 32 * (r % 352) + n4; sc = ((n >> 7) & 1) * DFF + (n >> 8) * 128 + (n & 127); W = a.w_up; nsrc = 2 * DFF; WT = a.WupT; ldt = 2048; ks = a.ffn_g; }
;     else if ((r -= F_UP) < F_DN) { kb = r >> 6; n = 32 * (r & 63) + n4; sc = n; W = a.w_dn; nsrc = 2048; WT = a.WdT; ldt = DFF; ks = nullptr; }
;     else if ((r -= F_DN) < F_IN) { kb = r >> 7; n = 32 * (r & 127) + n4;
;         if (n < 1024) sc = n; else if (n < 2048) sc = n + 64; else sc = (((n >> 7) & 1) ? 3136 : 2112) + 128 * ((n - 2048) >> 8) + (n & 127);
;         W = a.w_in; nsrc = INW; WT = a.WinT; ldt = 2048; ks = a.attn_g; }
;     else if ((r -= F_IN) < F_Q) { kb = r >> 5; n = 32 * (6 * ((r & 31) >> 2) + (r & 3)) + n4; sc = n; W = a.w_qb; nsrc = 1536; WT = a.WqT; ldt = 2048; ks = a.qa_g; d.gs = QSCALE; }
;     else { r -= F_Q; kb = r >> 6; n = 32 * (r & 63) + n4; sc = n; W = a.w_kvb; nsrc = 2048; WT = a.WkvT; ldt = 2048; ks = a.kva_g; }
;     const int k0 = 64 * kb + 8 * kk;
;     d.src = W + (size_t)k0 * nsrc + sc; d.nsrc = nsrc; d.dst = WT + (size_t)n * ldt + k0; d.ldt = ldt; d.ks = ks ? ks + k0 : nullptr;
;     return d;
; }
; __device__ __forceinline__ int p0_super(int s, int q) {
;     int base, nbw;
;     if (s < F_O / 4) { base = 0; nbw = 64; }
;     else if ((s -= F_O / 4) < F_UP / 4) { base = F_O; nbw = 352; }
;     else if ((s -= F_UP / 4) < F_DN / 4) { base = F_O + F_UP; nbw = 64; }
;     else if ((s -= F_DN / 4) < F_IN / 4) { base = F_O + F_UP + F_DN; nbw = 128; }
;     else if ((s -= F_IN / 4) < F_Q / 4) { base = F_O + F_UP + F_DN + F_IN; nbw = 32; }
;     else { s -= F_Q / 4; base = F_O + F_UP + F_DN + F_IN + F_Q; nbw = 64; }
;     return base + ((s / nbw) * 4 + q) * nbw + (s % nbw);
; }
; template <int NB>
; __device__ __forceinline__ void p0_batch(int it0, int stride, int lane, const P0Ptrs& a) {
;     f32x4 v[NB][8], s0[NB], s1[NB]; P0Desc d[NB];
; #pragma unroll
.LBB0_759:
	v_lshl_add_u64 v[112:113], s[28:29], 0, v[146:147]
	s_mov_b64 s[54:55], 0x18fc0000
	s_mov_b32 m0, s78
	v_lshl_add_u64 v[100:101], v[112:113], 0, s[54:55]
	s_waitcnt vmcnt(0)
	s_barrier
	global_load_lds_dwordx4 v[100:101], off
	v_lshl_add_u64 v[100:101], v[112:113], 0, s[38:39]
	s_add_i32 m0, s78, 0x2000
	v_lshl_add_u64 v[136:137], s[28:29], 0, v[144:145]
	global_load_lds_dwordx4 v[100:101], off
	v_lshl_add_u64 v[100:101], v[136:137], 0, s[40:41]
	s_add_i32 m0, s78, 0x4000
	v_lshl_add_u64 v[134:135], s[28:29], 0, v[148:149]
	global_load_lds_dwordx4 v[100:101], off
	v_lshl_add_u64 v[100:101], v[134:135], 0, s[42:43]
	s_mov_b32 m0, s58
	global_load_lds_dwordx4 v[100:101], off
	v_lshl_add_u64 v[100:101], v[134:135], 0, s[44:45]
	s_mov_b32 m0, s77
	global_load_lds_dwordx4 v[100:101], off
	s_cmp_gt_u32 s87, 20
	s_cbranch_scc1 .Lcv_done
	s_cmp_eq_u32 s87, 0
	s_cbranch_scc1 .Lcv_nocons
	s_cmp_gt_u32 s32, 6
	s_cbranch_scc1 .Lcv_nomul
	v_mul_f32_e32 v240, v244, v240
	v_mul_f32_e32 v241, v244, v241
	v_mul_f32_e32 v242, v244, v242
	v_mul_f32_e32 v243, v244, v243
	v_mul_f32_e32 v250, v245, v250
	v_mul_f32_e32 v251, v245, v251
	v_mul_f32_e32 v252, v245, v252
	v_mul_f32_e32 v253, v245, v253
.Lcv_nomul:
	v_cvt_pk_bf16_f32 v240, v240, v250
	v_cvt_pk_bf16_f32 v241, v241, v251
	v_cvt_pk_bf16_f32 v242, v242, v252
	v_cvt_pk_bf16_f32 v243, v243, v253
	global_store_dword v238, v240, s[92:93]
	s_add_u32 s98, s92, s91
	s_addc_u32 s99, s93, 0
	global_store_dword v238, v241, s[98:99]
	s_add_u32 s98, s98, s91
	s_addc_u32 s99, s99, 0
	global_store_dword v238, v242, s[98:99]
	s_add_u32 s98, s98, s91
	s_addc_u32 s99, s99, 0
	global_store_dword v238, v243, s[98:99]
	s_add_u32 s92, s92, 4
	s_addc_u32 s93, s93, 0
.Lcv_nocons:
	s_cmp_gt_u32 s87, 19
	s_cbranch_scc1 .Lcv_inc
	s_and_b32 s98, s87, 3
	s_cmp_lg_u32 s98, 0
	s_cbranch_scc1 .Lcv_loads
	s_add_i32 s32, s32, 1
	v_readfirstlane_b32 s99, v0
	s_waitcnt lgkmcnt(0)
	s_and_b32 s98, s2, 0xff
	s_lshr_b32 s90, s98, 3
	s_and_b32 s98, s98, 7
	s_lshl_b32 s98, s98, 3
	s_lshr_b32 s99, s99, 6
	s_add_i32 s91, s98, s99
	v_bfe_u32 v246, v0, 3, 3
	v_and_b32_e32 v254, 7, v0
	v_lshlrev_b32_e32 v239, 5, v246
	s_cmp_eq_u32 s32, 0
	s_cbranch_scc1 .Lcv_t0
	s_cmp_lt_u32 s32, 7
	s_cbranch_scc1 .Lcv_t1
	s_add_i32 s98, s32, -7
	s_lshl_b32 s98, s98, 5
	s_add_i32 s90, s90, s98
	s_cmp_ge_u32 s90, 0x58
	s_cselect_b32 s98, 32, 0
	s_sub_i32 s90, s90, s98
	s_lshl_b32 s98, s90, 19
	s_lshl_b32 s99, s91, 7
	s_add_i32 s98, s98, s99
	s_add_u32 s88, s88, s98
	s_addc_u32 s89, s89, 0
	s_mul_i32 s98, s91, 0x58000
	s_lshl_b32 s99, s90, 7
	s_add_i32 s98, s98, s99
	s_add_i32 s98, s98, 0x6900000
	s_add_u32 s92, s28, s98
	s_addc_u32 s93, s29, 0
	s_mov_b32 s90, 0x2000
	s_mov_b32 s91, 0x2c00
	v_lshlrev_b32_e32 v237, 16, v246
	v_lshl_add_u32 v237, v254, 4, v237
	v_mul_u32_u24_e32 v238, 0xb000, v254
	v_lshl_add_u32 v238, v246, 4, v238
	s_branch .Lcv_s2done
.Lcv_t1:
	s_add_i32 s98, s32, -1
	s_lshl_b32 s98, s98, 6
	s_add_i32 s91, s91, s98
	s_cmp_ge_u32 s91, 0x160
	s_cselect_b32 s98, 64, 0
	s_sub_i32 s91, s91, s98
	s_bfe_u32 s98, s91, 0x10002
	s_mul_i32 s98, s98, 0x5800
	s_lshr_b32 s99, s91, 3
	s_lshl_b32 s99, s99, 9
	s_add_i32 s98, s98, s99
	s_and_b32 s99, s91, 3
	s_lshl_b32 s99, s99, 7
	s_add_i32 s98, s98, s99
	s_mul_i32 s99, s90, 0x2c0000
	s_add_i32 s98, s98, s99
	s_add_u32 s88, s88, s98
	s_addc_u32 s89, s89, 0
	s_lshl_b32 s98, s90, 8
	s_add_u32 s94, s94, s98
	s_addc_u32 s95, s95, 0
	s_lshl_b32 s98, s91, 17
	s_lshl_b32 s99, s90, 7
	s_add_i32 s98, s98, s99
	s_add_i32 s98, s98, 0x3d00000
	s_add_u32 s92, s28, s98
	s_addc_u32 s93, s29, 0
	s_mov_b32 s90, 0xb000
	s_mov_b32 s91, 0x1000
	v_mul_u32_u24_e32 v237, 0x58000, v246
	v_lshl_add_u32 v237, v254, 4, v237
	v_lshlrev_b32_e32 v238, 14, v254
	v_lshl_add_u32 v238, v246, 4, v238
	s_branch .Lcv_s2done
.Lcv_t0:
	s_lshl_b32 s98, s90, 19
	s_lshl_b32 s99, s91, 7
	s_add_i32 s98, s98, s99
	s_add_u32 s88, s88, s98
	s_addc_u32 s89, s89, 0
	s_lshl_b32 s98, s90, 8
	s_cmp_lt_u32 s90, 16
	s_cselect_b32 s99, 0, 0x1000
	s_sub_i32 s98, s98, s99
	s_add_u32 s94, s94, s98
	s_addc_u32 s95, s95, 0
	s_lshl_b32 s98, s91, 17
	s_lshl_b32 s99, s90, 7
	s_add_i32 s98, s98, s99
	s_add_i32 s98, s98, 0x3500000
	s_add_u32 s92, s28, s98
	s_addc_u32 s93, s29, 0
	s_mov_b32 s90, 0x2000
	s_mov_b32 s91, 0x1000
	v_lshlrev_b32_e32 v237, 16, v246
	v_lshl_add_u32 v237, v254, 4, v237
	v_lshlrev_b32_e32 v238, 14, v254
	v_lshl_add_u32 v238, v246, 4, v238
.Lcv_s2done:
.Lcv_loads:
	global_load_dwordx4 v[240:243], v237, s[88:89] nt
	s_add_u32 s98, s88, s90
	s_addc_u32 s99, s89, 0
	global_load_dwordx4 v[250:253], v237, s[98:99] nt
	s_cmp_gt_u32 s32, 6
	s_cbranch_scc1 .Lcv_nogl
	global_load_dwordx2 v[244:245], v239, s[94:95]
	s_add_u32 s94, s94, 8
	s_addc_u32 s95, s95, 0
.Lcv_nogl:
	s_lshl_b32 s98, s90, 1
	s_add_u32 s88, s88, s98
	s_addc_u32 s89, s89, 0
	s_and_b32 s98, s87, 3
	s_cmp_lg_u32 s98, 3
	s_cbranch_scc1 .Lcv_inc
	s_cmp_gt_u32 s87, 18
	s_cbranch_scc1 .Lcv_inc
	s_add_i32 s99, s32, 1
	s_movk_i32 s98, 0x78
	s_cmp_lt_u32 s99, 7
	s_cselect_b32 s98, 0x60, s98
	s_cmp_eq_u32 s99, 0
	s_cselect_b32 s98, 0x50, s98
	s_cselect_b32 s99, 0, 0x58
	s_load_dwordx2 s[88:89], s[100:101], s98
	s_cmp_eq_u32 s99, 0
	s_cbranch_scc0 .Lcv_s1b_s
	s_bfe_u32 s99, s2, 0x50003
	s_cmp_lt_u32 s99, 16
	s_cselect_b32 s99, 64, 0x48
.Lcv_s1b_s:
	s_load_dwordx2 s[94:95], s[100:101], s99
.Lcv_inc:
	s_add_i32 s87, s87, 1
; template <int G> __device__ __forceinline__ void fin_gap(f32x16& P0, f32x16& P1, float (&sacc)[4], unsigned (&cv)[16], u32x4 (&pw)[4]) {
;   if constexpr (G < 16) { P1[G] = __builtin_amdgcn_exp2f(P1[G]); sacc[G & 3] += P0[G]; }
;   else { constexpr int r = 2 * (G - 16); sacc[r & 3] += P1[r]; sacc[(r + 1) & 3] += P1[r + 1]; }
;   if constexpr (G < 4) cv[G] = cvtpk_c(P0[2 * G], P0[2 * G + 1]);
;   else if constexpr (G >= 6 && G < 10) { constexpr int i = G - 2; cv[i] = cvtpk_c(P0[2 * i], P0[2 * i + 1]); }
;   else if constexpr (G >= 12 && G < 16) { constexpr int i = G - 4, j = i - 8; cv[i] = cvtpk_c(P1[2 * j], P1[2 * j + 1]); }
;   else if constexpr (G >= 18 && G < 22) { constexpr int i = G - 6, j = i - 8; cv[i] = cvtpk_c(P1[2 * j], P1[2 * j + 1]); }
;   if constexpr (G == 4 || G == 10 || G == 16 || G == 22) { constexpr int q = (G - 4) / 6; auto r0 = __builtin_amdgcn_permlane32_swap(cv[4 * q], cv[4 * q + 2], false, false); pw[q].x = r0[0]; pw[q].z = r0[1]; }
;   if constexpr (G == 5 || G == 11 || G == 17 || G == 23) { constexpr int q = (G - 5) / 6; auto r1 = __builtin_amdgcn_permlane32_swap(cv[4 * q + 1], cv[4 * q + 3], false, false); pw[q].y = r1[0]; pw[q].w = r1[1]; }
; }
.Lcv_done:
	v_exp_f32_e32 v1, v249
	v_exp_f32_e32 v101, v84
	v_exp_f32_e32 v103, v85
	v_exp_f32_e32 v205, v89
	v_exp_f32_e32 v206, v90
	v_sub_f32_e32 v102, v70, v140
	v_sub_f32_e32 v204, v74, v140
	v_exp_f32_e32 v160, v88
	v_sub_f32_e32 v88, v69, v140
	v_sub_f32_e32 v158, v72, v140
	v_exp_f32_e32 v154, v86
	v_exp_f32_e32 v159, v87
	v_exp_f32_e32 v208, v91
	v_exp_f32_e32 v209, v92
	v_exp_f32_e32 v210, v93
	v_exp_f32_e32 v211, v94
	v_sub_f32_e32 v155, v71, v140
	v_sub_f32_e32 v161, v73, v140
	v_sub_f32_e32 v207, v75, v140
	ds_read_b128 v[68:71], v178 offset:32768
	ds_read_b128 v[84:87], v178 offset:36864
	s_waitcnt lgkmcnt(0)
	ds_read_b128 v[104:107], v179 offset:32768
	ds_read_b128 v[108:111], v179 offset:36864
	v_mfma_f32_32x32x16_bf16 v[68:83], v[68:71], v[126:129], 0
	v_cvt_pk_bf16_f32 v100, v1, v101
	v_exp_f32_e32 v226, v99
	v_add_f32_e32 v227, 0, v1
	v_exp_f32_e32 v1, v88
	v_mfma_f32_32x32x16_bf16 v[84:99], v[84:87], v[126:129], 0
	v_add_f32_e32 v228, 0, v101
	v_cvt_pk_bf16_f32 v101, v103, v154
	s_waitcnt lgkmcnt(0)
	ds_read_b128 v[130:133], v177 offset:32768
	ds_read_b128 v[150:153], v177 offset:36864
	v_mfma_f32_32x32x16_bf16 v[68:83], v[104:107], v[122:125], v[68:83]
	v_exp_f32_e32 v229, v102
	v_cvt_pk_bf16_f32 v102, v159, v160
	v_add_f32_e32 v230, 0, v103
	v_mfma_f32_32x32x16_bf16 v[84:99], v[108:111], v[122:125], v[84:99]
	v_add_f32_e32 v105, 0, v154
	v_cvt_pk_bf16_f32 v103, v205, v206
	v_exp_f32_e32 v231, v155
	s_waitcnt lgkmcnt(0)
	ds_read_b128 v[106:109], v176 offset:32768
	ds_read_b128 v[154:157], v176 offset:36864
	v_mfma_f32_32x32x16_bf16 v[68:83], v[130:133], v[118:121], v[68:83]
	v_permlane32_swap_b32_e32 v100, v102
	v_exp_f32_e32 v232, v158
	v_add_f32_e32 v227, v159, v227
	v_mfma_f32_32x32x16_bf16 v[84:99], v[150:153], v[118:121], v[84:99]
	v_permlane32_swap_b32_e32 v101, v103
	v_exp_f32_e32 v233, v161
	v_add_f32_e32 v228, v160, v228
	s_waitcnt lgkmcnt(0)
	ds_read_b128 v[130:133], v178 offset:40960
	ds_read_b128 v[150:153], v178 offset:45056
	ds_read_b128 v[158:161], v171
	v_mfma_f32_32x32x16_bf16 v[68:83], v[106:109], v[114:117], v[68:83]
	v_cvt_pk_bf16_f32 v104, v208, v209
	v_exp_f32_e32 v234, v204
	v_add_f32_e32 v230, v205, v230
	v_mfma_f32_32x32x16_bf16 v[84:99], v[154:157], v[114:117], v[84:99]
	v_add_f32_e32 v236, v206, v105
	v_cvt_pk_bf16_f32 v105, v210, v211
	v_exp_f32_e32 v235, v207
	s_waitcnt lgkmcnt(0)
	ds_read_b128 v[108:111], v179 offset:40960
	ds_read_b128 v[154:157], v179 offset:45056
	ds_read_b128 v[204:207], v170
	v_mfma_f32_32x32x16_bf16 v[68:83], v[130:133], v[158:161], v[68:83]
	v_cvt_pk_bf16_f32 v106, v212, v213
	v_exp_f32_e32 v216, v216
	v_add_f32_e32 v227, v208, v227
	v_mfma_f32_32x32x16_bf16 v[84:99], v[150:153], v[158:161], v[84:99]
	v_cvt_pk_bf16_f32 v107, v214, v215
	v_exp_f32_e32 v217, v217
	v_add_f32_e32 v228, v209, v228
	s_waitcnt lgkmcnt(0)
	ds_read_b128 v[130:133], v177 offset:40960
	ds_read_b128 v[150:153], v177 offset:45056
	ds_read_b128 v[158:161], v169
	v_mfma_f32_32x32x16_bf16 v[68:83], v[108:111], v[204:207], v[68:83]
	v_permlane32_swap_b32_e32 v104, v106
	v_exp_f32_e32 v218, v218
	v_add_f32_e32 v230, v210, v230
	v_mfma_f32_32x32x16_bf16 v[84:99], v[154:157], v[204:207], v[84:99]
	v_add_f32_e32 v111, v211, v236
	v_permlane32_swap_b32_e32 v105, v107
	v_exp_f32_e32 v219, v219
	s_waitcnt lgkmcnt(0)
	ds_read_b128 v[154:157], v176 offset:40960
	ds_read_b128 v[204:207], v176 offset:45056
	ds_read_b128 v[208:211], v168
	v_mfma_f32_32x32x16_bf16 v[68:83], v[130:133], v[158:161], v[68:83]
	v_cvt_pk_bf16_f32 v108, v226, v1
	v_exp_f32_e32 v220, v220
	v_add_f32_e32 v212, v212, v227
	v_mfma_f32_32x32x16_bf16 v[84:99], v[150:153], v[158:161], v[84:99]
	v_cvt_pk_bf16_f32 v109, v229, v231
	v_exp_f32_e32 v221, v221
	v_add_f32_e32 v213, v213, v228
	s_waitcnt lgkmcnt(0)
	ds_read_b128 v[130:133], v178 offset:49152
	ds_read_b128 v[150:153], v178 offset:53248
	ds_read_b128 v[158:161], v171 offset:4096
	v_mfma_f32_32x32x16_bf16 v[68:83], v[154:157], v[208:211], v[68:83]
	v_cvt_pk_bf16_f32 v110, v232, v233
	v_exp_f32_e32 v222, v222
	v_add_f32_e32 v214, v214, v230
	v_mfma_f32_32x32x16_bf16 v[84:99], v[204:207], v[208:211], v[84:99]
	v_add_f32_e32 v215, v215, v111
	v_cvt_pk_bf16_f32 v111, v234, v235
	v_exp_f32_e32 v223, v223
	s_waitcnt lgkmcnt(0)
	ds_read_b128 v[154:157], v179 offset:49152
	ds_read_b128 v[204:207], v179 offset:53248
	ds_read_b128 v[208:211], v170 offset:4096
	v_mfma_f32_32x32x16_bf16 v[68:83], v[130:133], v[158:161], v[68:83]
	v_add_f32_e32 v1, v1, v213
	v_permlane32_swap_b32_e32 v108, v110
	v_add_f32_e32 v226, v226, v212
	v_mfma_f32_32x32x16_bf16 v[84:99], v[150:153], v[158:161], v[84:99]
	v_add_f32_e32 v131, v229, v214
	v_add_f32_e32 v132, v231, v215
	v_permlane32_swap_b32_e32 v109, v111
	s_waitcnt lgkmcnt(0)
	ds_read_b128 v[150:153], v177 offset:49152
	ds_read_b128 v[158:161], v177 offset:53248
	ds_read_b128 v[212:215], v169 offset:4096
	v_mfma_f32_32x32x16_bf16 v[68:83], v[154:157], v[208:211], v[68:83]
	v_add_f32_e32 v133, v232, v226
	v_add_f32_e32 v1, v233, v1
	v_cvt_pk_bf16_f32 v130, v216, v217
	v_mfma_f32_32x32x16_bf16 v[84:99], v[204:207], v[208:211], v[84:99]
	v_add_f32_e32 v226, v234, v131
	v_cvt_pk_bf16_f32 v131, v218, v219
	v_add_f32_e32 v227, v235, v132
	s_waitcnt lgkmcnt(0)
	ds_read_b128 v[154:157], v176 offset:49152
	ds_read_b128 v[204:207], v176 offset:53248
	ds_read_b128 v[208:211], v168 offset:4096
	v_mfma_f32_32x32x16_bf16 v[68:83], v[150:153], v[212:215], v[68:83]
	v_add_f32_e32 v1, v217, v1
	v_cvt_pk_bf16_f32 v132, v220, v221
	v_add_f32_e32 v216, v216, v133
	v_mfma_f32_32x32x16_bf16 v[84:99], v[158:161], v[212:215], v[84:99]
	v_cvt_pk_bf16_f32 v133, v222, v223
	v_add_f32_e32 v150, v218, v226
	v_add_f32_e32 v151, v219, v227
	s_waitcnt lgkmcnt(0)
	v_mfma_f32_32x32x16_bf16 v[68:83], v[154:157], v[208:211], v[68:83]
	v_add_f32_e32 v1, v221, v1
	v_permlane32_swap_b32_e32 v130, v132
	v_add_f32_e32 v152, v220, v216
	v_mfma_f32_32x32x16_bf16 v[84:99], v[204:207], v[208:211], v[84:99]
	v_permlane32_swap_b32_e32 v131, v133
	v_add_f32_e32 v150, v222, v150
	v_add_f32_e32 v151, v223, v151
	v_add_f32_e32 v1, v152, v1
	v_add_f32_e32 v150, v150, v151
	v_add_f32_e32 v205, v1, v150
	v_mov_b32_e32 v206, v205
	s_nop 1
	v_permlane32_swap_b32_e32 v205, v206
